# RET chunked scan: LDS reads prefetched up to 12 ahead into spare registers, counted lgkmcnt (same transformation as the SSD scan)
# speedup vs baseline: 1.0454x; 1.0124x over previous
; template <int MIX>
; __device__ __forceinline__ void ch_scan(f32x4 (&St)[ChCfg<MIX>::K / 16], LAS unsigned char* B, int vg, int lane) {
;     typedef ChCfg<MIX> C; typedef RecCfg<MIX> RC; constexpr int K = C::K;
;     const int r = lane & 15, h = lane >> 4;
;     const LAS float* Gt = (const LAS float*)(B + C::B_G);
;     LAS float* Of = (LAS float*)B + RC::OFF_O;
; #pragma unroll
;     for (int mc = 0; mc < 4; ++mc) {
;         const int t0 = mc * 16;
;         f32x4 X = (f32x4){0.f, 0.f, 0.f, 0.f};
; #pragma unroll
;         for (int kb = 0; kb < K / 32; ++kb) {
;             const f16x8 a = *(const LAS f16x8*)(B + C::B_KH + (t0 + r) * C::RS + (kb * 32 + 8 * h) * 2);
;             const f16x8 b = *(const LAS f16x8*)(B + C::B_QH + (t0 + r) * C::RS + (kb * 32 + 8 * h) * 2);
;             X = __builtin_amdgcn_mfma_f32_16x16x32_f16(a, b, X, 0, 0, 0); }
;         const float gi = Gt[t0 + r]; const f32x4 gj = *(const LAS f32x4*)(Gt + t0 + 4 * h);
;         f16x8 pa, vb;
; #pragma unroll
;         for (int e = 0; e < 4; ++e) { const float d = fminf(gi - gj[e], 0.f); const float pv = (4 * h + e <= r) ? X[e] * __expf(d) : 0.f; pa[e] = (f16_t)pv; pa[4 + e] = (f16_t)0.f; }
;         { const u32x2 vv = *(const LAS u32x2*)(B + C::B_VT + (16 * vg + r) * C::TS_ + (t0 + 4 * h) * 2);
;           const u32x4 v4 = (u32x4){vv.x, vv.y, 0u, 0u}; vb = __builtin_bit_cast(f16x8, v4); }
;         f32x4 O = __builtin_amdgcn_mfma_f32_16x16x32_f16(pa, vb, (f32x4){0.f, 0.f, 0.f, 0.f}, 0, 0, 0);
; #pragma unroll
;         for (int m = 0; m < K / 32; ++m) {
;             const u32x2 qa0 = *(const LAS u32x2*)(B + C::B_QT + (t0 + r) * C::RS + (32 * m + 4 * h) * 2), qa1 = *(const LAS u32x2*)(B + C::B_QT + (t0 + r) * C::RS + (32 * m + 16 + 4 * h) * 2);
;             const u32x4 qa4 = (u32x4){qa0.x, qa0.y, qa1.x, qa1.y};
;             const u32x4 sb4 = (u32x4){pkh(St[2 * m][0], St[2 * m][1]), pkh(St[2 * m][2], St[2 * m][3]), pkh(St[2 * m + 1][0], St[2 * m + 1][1]), pkh(St[2 * m + 1][2], St[2 * m + 1][3])};
;             O = __builtin_amdgcn_mfma_f32_16x16x32_f16(__builtin_bit_cast(f16x8, qa4), __builtin_bit_cast(f16x8, sb4), O, 0, 0, 0); }
; #pragma unroll
;         for (int e = 0; e < 4; ++e) Of[(t0 + 4 * h + e) * 32 + 16 * vg + r] = O[e];
;         const float ge = __expf(Gt[t0 + 15]);
; #pragma unroll
;         for (int kt = 0; kt < K / 16; ++kt) {
.LBB0_264:
	s_andn2_b64 vcc, exec, s[6:7]
	s_cbranch_vccnz .LBB0_259
	v_add_u32_e32 v150, v47, v42
	ds_read_b128 v[146:149], v150 offset:9216
	ds_read_b128 v[154:157], v150
	ds_read_b128 v[158:161], v150 offset:9280
	ds_read_b128 v[162:165], v150 offset:64
	ds_read_b32 v166, v57 offset:41472
	v_add_u32_e32 v174, v45, v44
	ds_read_b128 v[170:173], v174 offset:41472
	v_add_u32_e32 v182, v43, v44
	v_mov_b32_e32 v180, 0
	v_mov_b32_e32 v181, 0
	ds_read_b64 v[178:179], v182 offset:36864
	v_cvt_pk_f16_f32 v82, v8, v9
	v_cvt_pk_f16_f32 v83, v10, v11
	v_cvt_pk_f16_f32 v84, v18, v19
	v_cvt_pk_f16_f32 v85, v20, v21
	s_waitcnt lgkmcnt(5)
	v_mfma_f32_16x16x32_f16 v[22:25], v[146:149], v[154:157], 0
	s_waitcnt lgkmcnt(3)
	v_mfma_f32_16x16x32_f16 v[22:25], v[158:161], v[162:165], v[22:25]
	v_add_u32_e32 v70, v45, v48
	s_waitcnt lgkmcnt(1)
	v_sub_f32_e32 v15, v166, v170
	v_min_f32_e32 v15, 0, v15
	v_mul_f32_e32 v15, 0x3fb8aa3b, v15
	v_exp_f32_e32 v15, v15
	v_add_u32_e32 v72, v45, v46
	v_add_u32_e32 v190, 0x4800, v72
	ds_read2_b64 v[186:189], v190 offset1:4
	ds_read2_b64 v[194:197], v190 offset0:8 offset1:12
	ds_read_b32 v198, v17 offset:41532
	v_mov_b32_e32 v232, 0
	v_mov_b32_e32 v233, 0
	ds_read_b64 v[230:231], v72 offset:27648
	v_mov_b32_e32 v236, 0
	v_mov_b32_e32 v237, 0
	ds_read_b64 v[234:235], v72 offset:29952
	v_mov_b32_e32 v240, 0
	v_mov_b32_e32 v241, 0
	ds_read_b64 v[238:239], v72 offset:32256
	v_mov_b32_e32 v244, 0
	v_mov_b32_e32 v245, 0
	ds_read_b64 v[242:243], v70 offset:27648
	ds_read_b128 v[246:249], v60 offset:9216
	ds_read_b128 v[150:153], v60
	v_fma_mixlo_f16 v15, v22, v15, 0
	v_cndmask_b32_e64 v16, v15, 0, s[42:43]
	v_sub_f32_e32 v15, v166, v171
	v_min_f32_e32 v15, 0, v15
	v_mul_f32_e32 v15, 0x3fb8aa3b, v15
	v_exp_f32_e32 v15, v15
	v_add_u32_e32 v73, v51, v46
	v_fma_mixlo_f16 v15, v23, v15, 0
	v_cndmask_b32_e64 v22, 0, v15, s[44:45]
	v_sub_f32_e32 v15, v166, v172
	v_sub_f32_e32 v14, v166, v173
	ds_read_b128 v[182:185], v60 offset:9280
	ds_read_b128 v[146:149], v60 offset:64
	v_min_f32_e32 v15, 0, v15
	v_min_f32_e32 v14, 0, v14
	v_mul_f32_e32 v15, 0x3fb8aa3b, v15
	v_mul_f32_e32 v14, 0x3fb8aa3b, v14
	v_exp_f32_e32 v15, v15
	v_exp_f32_e32 v14, v14
	v_fma_mixlo_f16 v15, v24, v15, 0
	v_fma_mixlo_f16 v14, v25, v14, 0
	v_cndmask_b32_e64 v15, v15, 0, s[46:47]
	v_cndmask_b32_e64 v14, v14, 0, s[48:49]
	v_pack_b32_f16 v15, v15, v14
	v_pack_b32_f16 v14, v16, v22
	v_mov_b32_e32 v16, v17
	v_mov_b32_e32 v24, v17
	v_mov_b32_e32 v25, v17
	s_nop 0
	s_waitcnt lgkmcnt(11)
	v_mfma_f32_16x16x32_f16 v[74:77], v[14:17], v[178:181], 0
	s_waitcnt lgkmcnt(10)
	v_mfma_f32_16x16x32_f16 v[74:77], v[186:189], v[82:85], v[74:77]
	ds_read_b32 v154, v49 offset:41536
	v_cvt_pk_f16_f32 v82, v4, v5
	v_cvt_pk_f16_f32 v83, v6, v7
	v_cvt_pk_f16_f32 v84, v0, v1
	v_cvt_pk_f16_f32 v85, v2, v3
	v_add_u32_e32 v14, 0xc400, v58
	s_waitcnt lgkmcnt(10)
	v_mfma_f32_16x16x32_f16 v[74:77], v[194:197], v[82:85], v[74:77]
	ds_read_b128 v[158:161], v174 offset:41536
	s_nop 7
	ds_write2_b32 v14, v74, v75 offset1:32
	ds_write_b32 v58, v76 offset:50432
	ds_write_b32 v59, v77 offset:50176
	s_waitcnt lgkmcnt(13)
	v_mul_f32_e32 v14, 0x3fb8aa3b, v198
	v_add_u32_e32 v190, v43, v50
	v_mov_b32_e32 v164, 0
	v_mov_b32_e32 v165, 0
	ds_read_b64 v[162:163], v190 offset:36864
	v_exp_f32_e32 v74, v14
	s_nop 0
	v_pk_mul_f32 v[10:11], v[10:11], v[74:75] op_sel_hi:[1,0]
	v_pk_mul_f32 v[8:9], v[8:9], v[74:75] op_sel_hi:[1,0]
	v_pk_mul_f32 v[20:21], v[20:21], v[74:75] op_sel_hi:[1,0]
	v_pk_mul_f32 v[18:19], v[18:19], v[74:75] op_sel_hi:[1,0]
	s_waitcnt lgkmcnt(13)
	v_mfma_f32_16x16x32_f16 v[8:11], v[230:233], v[178:181], v[8:11]
	v_add_u32_e32 v170, 0x5000, v72
	ds_read2_b64 v[166:169], v170 offset0:32 offset1:36
	v_pk_mul_f32 v[6:7], v[6:7], v[74:75] op_sel_hi:[1,0]
	v_pk_mul_f32 v[4:5], v[4:5], v[74:75] op_sel_hi:[1,0]
	s_waitcnt lgkmcnt(13)
	v_mfma_f32_16x16x32_f16 v[18:21], v[234:237], v[178:181], v[18:21]
	ds_read2_b64 v[186:189], v170 offset0:40 offset1:44
	v_pk_mul_f32 v[2:3], v[2:3], v[74:75] op_sel_hi:[1,0]
	v_pk_mul_f32 v[0:1], v[0:1], v[74:75] op_sel_hi:[1,0]
	s_waitcnt lgkmcnt(13)
	v_mfma_f32_16x16x32_f16 v[4:7], v[238:241], v[178:181], v[4:7]
	ds_read_b32 v194, v17 offset:41596
	v_cvt_pk_f16_f32 v82, v8, v9
	v_cvt_pk_f16_f32 v83, v10, v11
	s_waitcnt lgkmcnt(13)
	v_mfma_f32_16x16x32_f16 v[0:3], v[242:245], v[178:181], v[0:3]
	v_mov_b32_e32 v200, 0
	v_mov_b32_e32 v201, 0
	ds_read_b64 v[198:199], v73 offset:27648
	v_mov_b32_e32 v192, 0
	v_mov_b32_e32 v193, 0
	ds_read_b64 v[190:191], v73 offset:29952
	v_cvt_pk_f16_f32 v84, v18, v19
	v_cvt_pk_f16_f32 v85, v20, v21
	s_waitcnt lgkmcnt(13)
	v_mfma_f32_16x16x32_f16 v[22:25], v[246:249], v[150:153], 0
	v_mov_b32_e32 v232, 0
	v_mov_b32_e32 v233, 0
	ds_read_b64 v[230:231], v73 offset:32256
	v_add_u32_e32 v170, v51, v48
	v_mov_b32_e32 v236, 0
	v_mov_b32_e32 v237, 0
	ds_read_b64 v[234:235], v170 offset:27648
	s_waitcnt lgkmcnt(13)
	v_mfma_f32_16x16x32_f16 v[22:25], v[182:185], v[146:149], v[22:25]
	ds_read_b128 v[238:241], v63 offset:9216
	ds_read_b128 v[178:181], v63
	s_waitcnt lgkmcnt(13)
	v_sub_f32_e32 v15, v154, v158
	v_min_f32_e32 v15, 0, v15
	v_mul_f32_e32 v15, 0x3fb8aa3b, v15
	v_exp_f32_e32 v15, v15
	s_nop 0
	v_fma_mixlo_f16 v15, v22, v15, 0
	v_cndmask_b32_e64 v16, v15, 0, s[42:43]
	v_sub_f32_e32 v15, v154, v159
	v_min_f32_e32 v15, 0, v15
	v_mul_f32_e32 v15, 0x3fb8aa3b, v15
	v_exp_f32_e32 v15, v15
	s_nop 0
	v_fma_mixlo_f16 v15, v23, v15, 0
	v_cndmask_b32_e64 v22, 0, v15, s[44:45]
	v_sub_f32_e32 v15, v154, v160
	v_sub_f32_e32 v14, v154, v161
	ds_read_b128 v[242:245], v63 offset:9280
	ds_read_b128 v[246:249], v63 offset:64
	v_min_f32_e32 v15, 0, v15
	v_min_f32_e32 v14, 0, v14
	v_mul_f32_e32 v15, 0x3fb8aa3b, v15
	v_mul_f32_e32 v14, 0x3fb8aa3b, v14
	v_exp_f32_e32 v15, v15
	v_exp_f32_e32 v14, v14
	v_fma_mixlo_f16 v15, v24, v15, 0
	v_fma_mixlo_f16 v14, v25, v14, 0
	v_cndmask_b32_e64 v15, v15, 0, s[46:47]
	v_cndmask_b32_e64 v14, v14, 0, s[48:49]
	v_pack_b32_f16 v15, v15, v14
	v_pack_b32_f16 v14, v16, v22
	v_mov_b32_e32 v16, v17
	v_mov_b32_e32 v24, v17
	v_mov_b32_e32 v25, v17
	s_nop 0
	s_waitcnt lgkmcnt(11)
; #define LAS __attribute__((address_space(3)))
; template <int MIX>
; __device__ __forceinline__ void ch_scan(f32x4 (&St)[ChCfg<MIX>::K / 16], LAS unsigned char* B, int vg, int lane) {
;     ...
;     for (int mc = 0; mc < 4; ++mc) {
;         const int t0 = mc * 16;
;         f32x4 X = (f32x4){0.f, 0.f, 0.f, 0.f};
; #pragma unroll
;         for (int kb = 0; kb < K / 32; ++kb) {
;             const f16x8 a = *(const LAS f16x8*)(B + C::B_KH + (t0 + r) * C::RS + (kb * 32 + 8 * h) * 2);
;             const f16x8 b = *(const LAS f16x8*)(B + C::B_QH + (t0 + r) * C::RS + (kb * 32 + 8 * h) * 2);
;             X = __builtin_amdgcn_mfma_f32_16x16x32_f16(a, b, X, 0, 0, 0); }
;         const float gi = Gt[t0 + r]; const f32x4 gj = *(const LAS f32x4*)(Gt + t0 + 4 * h);
;         f16x8 pa, vb;
; #pragma unroll
;         for (int e = 0; e < 4; ++e) { const float d = fminf(gi - gj[e], 0.f); const float pv = (4 * h + e <= r) ? X[e] * __expf(d) : 0.f; pa[e] = (f16_t)pv; pa[4 + e] = (f16_t)0.f; }
;         { const u32x2 vv = *(const LAS u32x2*)(B + C::B_VT + (16 * vg + r) * C::TS_ + (t0 + 4 * h) * 2);
;           const u32x4 v4 = (u32x4){vv.x, vv.y, 0u, 0u}; vb = __builtin_bit_cast(f16x8, v4); }
;         f32x4 O = __builtin_amdgcn_mfma_f32_16x16x32_f16(pa, vb, (f32x4){0.f, 0.f, 0.f, 0.f}, 0, 0, 0);
; #pragma unroll
;         for (int m = 0; m < K / 32; ++m) {
;             const u32x2 qa0 = *(const LAS u32x2*)(B + C::B_QT + (t0 + r) * C::RS + (32 * m + 4 * h) * 2), qa1 = *(const LAS u32x2*)(B + C::B_QT + (t0 + r) * C::RS + (32 * m + 16 + 4 * h) * 2);
;             const u32x4 qa4 = (u32x4){qa0.x, qa0.y, qa1.x, qa1.y};
;             const u32x4 sb4 = (u32x4){pkh(St[2 * m][0], St[2 * m][1]), pkh(St[2 * m][2], St[2 * m][3]), pkh(St[2 * m + 1][0], St[2 * m + 1][1]), pkh(St[2 * m + 1][2], St[2 * m + 1][3])};
;             O = __builtin_amdgcn_mfma_f32_16x16x32_f16(__builtin_bit_cast(f16x8, qa4), __builtin_bit_cast(f16x8, sb4), O, 0, 0, 0); }
; #pragma unroll
;         for (int e = 0; e < 4; ++e) Of[(t0 + 4 * h + e) * 32 + 16 * vg + r] = O[e];
;         const float ge = __expf(Gt[t0 + 15]);
; #pragma unroll
;         for (int kt = 0; kt < K / 16; ++kt) {
;             const u32x2 ka0 = *(const LAS u32x2*)(B + C::B_KT + (16 * kt + r) * C::TS_ + (t0 + 4 * h) * 2);
;             const u32x4 ka4 = (u32x4){ka0.x, ka0.y, 0u, 0u};
	v_mfma_f32_16x16x32_f16 v[74:77], v[14:17], v[162:165], 0
	s_waitcnt lgkmcnt(10)
	v_mfma_f32_16x16x32_f16 v[74:77], v[166:169], v[82:85], v[74:77]
	ds_read_b32 v150, v49 offset:41600
	v_cvt_pk_f16_f32 v82, v4, v5
	v_cvt_pk_f16_f32 v83, v6, v7
	v_cvt_pk_f16_f32 v84, v0, v1
	v_cvt_pk_f16_f32 v85, v2, v3
	v_add_u32_e32 v14, 0xcc00, v58
	s_waitcnt lgkmcnt(10)
	v_mfma_f32_16x16x32_f16 v[74:77], v[186:189], v[82:85], v[74:77]
	ds_read_b128 v[170:173], v174 offset:41600
	s_nop 7
	ds_write_b32 v61, v74 offset:50176
	ds_write2_b32 v14, v75, v76 offset0:32 offset1:64
	ds_write_b32 v62, v77 offset:50176
	s_waitcnt lgkmcnt(13)
	v_mul_f32_e32 v14, 0x3fb8aa3b, v194
	v_add_u32_e32 v146, v43, v52
	v_mov_b32_e32 v184, 0
	v_mov_b32_e32 v185, 0
	ds_read_b64 v[182:183], v146 offset:36864
	v_exp_f32_e32 v74, v14
	s_nop 0
	v_pk_mul_f32 v[10:11], v[10:11], v[74:75] op_sel_hi:[1,0]
	v_pk_mul_f32 v[8:9], v[8:9], v[74:75] op_sel_hi:[1,0]
	v_pk_mul_f32 v[20:21], v[20:21], v[74:75] op_sel_hi:[1,0]
	v_pk_mul_f32 v[18:19], v[18:19], v[74:75] op_sel_hi:[1,0]
	s_waitcnt lgkmcnt(13)
	v_mfma_f32_16x16x32_f16 v[8:11], v[198:201], v[162:165], v[8:11]
	v_add_u32_e32 v158, 0x5800, v72
	ds_read2_b64 v[154:157], v158 offset0:64 offset1:68
	v_pk_mul_f32 v[6:7], v[6:7], v[74:75] op_sel_hi:[1,0]
	v_pk_mul_f32 v[4:5], v[4:5], v[74:75] op_sel_hi:[1,0]
	s_waitcnt lgkmcnt(13)
	v_mfma_f32_16x16x32_f16 v[18:21], v[190:193], v[162:165], v[18:21]
	ds_read2_b64 v[166:169], v158 offset0:72 offset1:76
	v_pk_mul_f32 v[2:3], v[2:3], v[74:75] op_sel_hi:[1,0]
	v_pk_mul_f32 v[0:1], v[0:1], v[74:75] op_sel_hi:[1,0]
	s_waitcnt lgkmcnt(13)
	v_mfma_f32_16x16x32_f16 v[4:7], v[230:233], v[162:165], v[4:7]
	ds_read_b32 v186, v17 offset:41660
	v_cvt_pk_f16_f32 v82, v8, v9
	s_waitcnt lgkmcnt(13)
	v_mfma_f32_16x16x32_f16 v[0:3], v[234:237], v[162:165], v[0:3]
	v_add_u32_e32 v146, v53, v46
	v_mov_b32_e32 v196, 0
	v_mov_b32_e32 v197, 0
	ds_read_b64 v[194:195], v146 offset:27648
	v_mov_b32_e32 v200, 0
	v_mov_b32_e32 v201, 0
	ds_read_b64 v[198:199], v146 offset:29952
	v_cvt_pk_f16_f32 v83, v10, v11
	v_cvt_pk_f16_f32 v84, v18, v19
	s_waitcnt lgkmcnt(13)
	v_mfma_f32_16x16x32_f16 v[22:25], v[238:241], v[178:181], 0
	v_mov_b32_e32 v192, 0
	v_mov_b32_e32 v193, 0
	ds_read_b64 v[190:191], v146 offset:32256
	v_add_u32_e32 v230, v53, v48
	v_mov_b32_e32 v160, 0
	v_mov_b32_e32 v161, 0
	ds_read_b64 v[158:159], v230 offset:27648
	v_cvt_pk_f16_f32 v85, v20, v21
	s_waitcnt lgkmcnt(13)
	v_mfma_f32_16x16x32_f16 v[22:25], v[242:245], v[246:249], v[22:25]
	v_add_u32_e32 v234, v54, v42
	ds_read_b128 v[162:165], v234 offset:9216
	ds_read_b128 v[238:241], v234
	s_waitcnt lgkmcnt(13)
	v_sub_f32_e32 v15, v150, v170
	v_min_f32_e32 v15, 0, v15
	v_mul_f32_e32 v15, 0x3fb8aa3b, v15
	v_exp_f32_e32 v15, v15
	s_nop 0
	v_fma_mixlo_f16 v15, v22, v15, 0
	v_cndmask_b32_e64 v16, v15, 0, s[42:43]
	v_sub_f32_e32 v15, v150, v171
	v_min_f32_e32 v15, 0, v15
	v_mul_f32_e32 v15, 0x3fb8aa3b, v15
	v_exp_f32_e32 v15, v15
	s_nop 0
	v_fma_mixlo_f16 v15, v23, v15, 0
	v_cndmask_b32_e64 v22, 0, v15, s[44:45]
	v_sub_f32_e32 v15, v150, v172
	v_sub_f32_e32 v14, v150, v173
	ds_read_b128 v[178:181], v234 offset:9280
	ds_read_b128 v[146:149], v234 offset:64
	v_min_f32_e32 v15, 0, v15
	v_min_f32_e32 v14, 0, v14
	v_mul_f32_e32 v15, 0x3fb8aa3b, v15
	v_mul_f32_e32 v14, 0x3fb8aa3b, v14
	v_exp_f32_e32 v15, v15
	v_exp_f32_e32 v14, v14
	v_fma_mixlo_f16 v15, v24, v15, 0
	v_fma_mixlo_f16 v14, v25, v14, 0
	v_cndmask_b32_e64 v15, v15, 0, s[46:47]
	v_cndmask_b32_e64 v14, v14, 0, s[48:49]
	v_pack_b32_f16 v15, v15, v14
	v_pack_b32_f16 v14, v16, v22
	v_mov_b32_e32 v16, v17
	v_mov_b32_e32 v24, v17
	v_mov_b32_e32 v25, v17
	s_nop 0
	s_waitcnt lgkmcnt(11)
	v_mfma_f32_16x16x32_f16 v[74:77], v[14:17], v[182:185], 0
	s_waitcnt lgkmcnt(10)
	v_mfma_f32_16x16x32_f16 v[72:75], v[154:157], v[82:85], v[74:77]
	ds_read_b32 v230, v66 offset:41472
	s_nop 3
	v_cvt_pk_f16_f32 v80, v4, v5
	v_cvt_pk_f16_f32 v81, v6, v7
	v_cvt_pk_f16_f32 v82, v0, v1
	v_cvt_pk_f16_f32 v83, v2, v3
	v_add_u32_e32 v14, 0xd400, v58
	s_waitcnt lgkmcnt(10)
	v_mfma_f32_16x16x32_f16 v[72:75], v[166:169], v[80:83], v[72:75]
	ds_read_b128 v[242:245], v174 offset:41664
	s_nop 7
	ds_write_b32 v64, v72 offset:50176
	ds_write2_b32 v14, v73, v74 offset0:32 offset1:64
	ds_write_b32 v65, v75 offset:50176
	s_waitcnt lgkmcnt(13)
; #define LAS __attribute__((address_space(3)))
; template <int MIX>
; __device__ __forceinline__ void ch_scan(f32x4 (&St)[ChCfg<MIX>::K / 16], LAS unsigned char* B, int vg, int lane) {
;     ...
;     for (int mc = 0; mc < 4; ++mc) {
;         const int t0 = mc * 16;
;         f32x4 X = (f32x4){0.f, 0.f, 0.f, 0.f};
; #pragma unroll
;         for (int kb = 0; kb < K / 32; ++kb) {
;             const f16x8 a = *(const LAS f16x8*)(B + C::B_KH + (t0 + r) * C::RS + (kb * 32 + 8 * h) * 2);
;             const f16x8 b = *(const LAS f16x8*)(B + C::B_QH + (t0 + r) * C::RS + (kb * 32 + 8 * h) * 2);
;             X = __builtin_amdgcn_mfma_f32_16x16x32_f16(a, b, X, 0, 0, 0); }
;         const float gi = Gt[t0 + r]; const f32x4 gj = *(const LAS f32x4*)(Gt + t0 + 4 * h);
;         f16x8 pa, vb;
; #pragma unroll
;         for (int e = 0; e < 4; ++e) { const float d = fminf(gi - gj[e], 0.f); const float pv = (4 * h + e <= r) ? X[e] * __expf(d) : 0.f; pa[e] = (f16_t)pv; pa[4 + e] = (f16_t)0.f; }
;         { const u32x2 vv = *(const LAS u32x2*)(B + C::B_VT + (16 * vg + r) * C::TS_ + (t0 + 4 * h) * 2);
;           const u32x4 v4 = (u32x4){vv.x, vv.y, 0u, 0u}; vb = __builtin_bit_cast(f16x8, v4); }
;         f32x4 O = __builtin_amdgcn_mfma_f32_16x16x32_f16(pa, vb, (f32x4){0.f, 0.f, 0.f, 0.f}, 0, 0, 0);
; #pragma unroll
;         for (int m = 0; m < K / 32; ++m) {
;             const u32x2 qa0 = *(const LAS u32x2*)(B + C::B_QT + (t0 + r) * C::RS + (32 * m + 4 * h) * 2), qa1 = *(const LAS u32x2*)(B + C::B_QT + (t0 + r) * C::RS + (32 * m + 16 + 4 * h) * 2);
;             const u32x4 qa4 = (u32x4){qa0.x, qa0.y, qa1.x, qa1.y};
;             const u32x4 sb4 = (u32x4){pkh(St[2 * m][0], St[2 * m][1]), pkh(St[2 * m][2], St[2 * m][3]), pkh(St[2 * m + 1][0], St[2 * m + 1][1]), pkh(St[2 * m + 1][2], St[2 * m + 1][3])};
;             O = __builtin_amdgcn_mfma_f32_16x16x32_f16(__builtin_bit_cast(f16x8, qa4), __builtin_bit_cast(f16x8, sb4), O, 0, 0, 0); }
; #pragma unroll
;         for (int e = 0; e < 4; ++e) Of[(t0 + 4 * h + e) * 32 + 16 * vg + r] = O[e];
;         const float ge = __expf(Gt[t0 + 15]);
; #pragma unroll
;         for (int kt = 0; kt < K / 16; ++kt) {
;             const u32x2 ka0 = *(const LAS u32x2*)(B + C::B_KT + (16 * kt + r) * C::TS_ + (t0 + 4 * h) * 2);
;             const u32x4 ka4 = (u32x4){ka0.x, ka0.y, 0u, 0u};
	v_mul_f32_e32 v14, 0x3fb8aa3b, v186
	v_add_u32_e32 v150, v43, v55
	v_mov_b32_e32 v248, 0
	v_mov_b32_e32 v249, 0
	ds_read_b64 v[246:247], v150 offset:36864
	v_exp_f32_e32 v72, v14
	s_nop 0
	v_pk_mul_f32 v[10:11], v[10:11], v[72:73] op_sel_hi:[1,0]
	v_pk_mul_f32 v[8:9], v[8:9], v[72:73] op_sel_hi:[1,0]
	v_pk_mul_f32 v[20:21], v[20:21], v[72:73] op_sel_hi:[1,0]
	v_pk_mul_f32 v[18:19], v[18:19], v[72:73] op_sel_hi:[1,0]
	s_waitcnt lgkmcnt(13)
	v_mfma_f32_16x16x32_f16 v[8:11], v[194:197], v[182:185], v[8:11]
	v_add_u32_e32 v234, 0x4800, v70
	ds_read2_b64 v[170:173], v234 offset1:4
	v_pk_mul_f32 v[6:7], v[6:7], v[72:73] op_sel_hi:[1,0]
	v_pk_mul_f32 v[4:5], v[4:5], v[72:73] op_sel_hi:[1,0]
	s_waitcnt lgkmcnt(13)
	v_mfma_f32_16x16x32_f16 v[18:21], v[198:201], v[182:185], v[18:21]
	ds_read2_b64 v[154:157], v234 offset0:8 offset1:12
	v_pk_mul_f32 v[2:3], v[2:3], v[72:73] op_sel_hi:[1,0]
	v_pk_mul_f32 v[0:1], v[0:1], v[72:73] op_sel_hi:[1,0]
	s_waitcnt lgkmcnt(13)
	v_mfma_f32_16x16x32_f16 v[4:7], v[190:193], v[182:185], v[4:7]
	ds_read_b32 v166, v17 offset:41724
	v_cvt_pk_f16_f32 v80, v8, v9
	s_waitcnt lgkmcnt(13)
	v_mfma_f32_16x16x32_f16 v[0:3], v[158:161], v[182:185], v[0:3]
	v_add_u32_e32 v186, v56, v46
	v_mov_b32_e32 v176, 0
	v_mov_b32_e32 v177, 0
	ds_read_b64 v[174:175], v186 offset:27648
	v_mov_b32_e32 v152, 0
	v_mov_b32_e32 v153, 0
	ds_read_b64 v[150:151], v186 offset:29952
	v_cvt_pk_f16_f32 v81, v10, v11
	s_waitcnt lgkmcnt(13)
	v_mfma_f32_16x16x32_f16 v[22:25], v[162:165], v[238:241], 0
	v_mov_b32_e32 v196, 0
	v_mov_b32_e32 v197, 0
	ds_read_b64 v[194:195], v186 offset:32256
	v_add_u32_e32 v234, v56, v48
	v_mov_b32_e32 v200, 0
	v_mov_b32_e32 v201, 0
	ds_read_b64 v[198:199], v234 offset:27648
	v_cvt_pk_f16_f32 v82, v18, v19
	v_cvt_pk_f16_f32 v83, v20, v21
	s_waitcnt lgkmcnt(13)
	v_mfma_f32_16x16x32_f16 v[22:25], v[178:181], v[146:149], v[22:25]
	s_waitcnt lgkmcnt(11)
	v_sub_f32_e32 v15, v230, v242
	v_min_f32_e32 v15, 0, v15
	v_mul_f32_e32 v15, 0x3fb8aa3b, v15
	v_exp_f32_e32 v15, v15
	s_nop 0
	s_nop 1
	v_fma_mixlo_f16 v15, v22, v15, 0
	v_cndmask_b32_e64 v16, v15, 0, s[42:43]
	v_sub_f32_e32 v15, v230, v243
	v_min_f32_e32 v15, 0, v15
	v_mul_f32_e32 v15, 0x3fb8aa3b, v15
	v_exp_f32_e32 v15, v15
	s_nop 0
	v_fma_mixlo_f16 v15, v23, v15, 0
	v_cndmask_b32_e64 v22, 0, v15, s[44:45]
	v_sub_f32_e32 v15, v230, v244
	v_sub_f32_e32 v14, v230, v245
	v_min_f32_e32 v15, 0, v15
	v_min_f32_e32 v14, 0, v14
	v_mul_f32_e32 v15, 0x3fb8aa3b, v15
	v_mul_f32_e32 v14, 0x3fb8aa3b, v14
	v_exp_f32_e32 v15, v15
	v_exp_f32_e32 v14, v14
	v_fma_mixlo_f16 v15, v24, v15, 0
	v_fma_mixlo_f16 v14, v25, v14, 0
	v_cndmask_b32_e64 v15, v15, 0, s[46:47]
	v_cndmask_b32_e64 v14, v14, 0, s[48:49]
	v_pack_b32_f16 v15, v15, v14
	v_pack_b32_f16 v14, v16, v22
	v_mov_b32_e32 v16, v17
	v_mov_b32_e32 v24, v17
	v_mov_b32_e32 v25, v17
	s_nop 0
	s_waitcnt lgkmcnt(7)
	v_mfma_f32_16x16x32_f16 v[72:75], v[14:17], v[246:249], 0
	s_waitcnt lgkmcnt(6)
	v_mfma_f32_16x16x32_f16 v[70:73], v[170:173], v[80:83], v[72:75]
	s_nop 3
	v_cvt_pk_f16_f32 v78, v4, v5
	v_cvt_pk_f16_f32 v79, v6, v7
	v_cvt_pk_f16_f32 v80, v0, v1
	v_cvt_pk_f16_f32 v81, v2, v3
	v_add_u32_e32 v14, 0xdc00, v58
	s_waitcnt lgkmcnt(5)
	v_mfma_f32_16x16x32_f16 v[70:73], v[154:157], v[78:81], v[70:73]
	s_nop 7
	ds_write_b32 v68, v70 offset:50176
	ds_write2_b32 v14, v71, v72 offset0:32 offset1:64
	ds_write_b32 v69, v73 offset:50176
	s_waitcnt lgkmcnt(7)
	v_mul_f32_e32 v14, 0x3fb8aa3b, v166
	v_exp_f32_e32 v70, v14
	s_nop 0
	v_pk_mul_f32 v[10:11], v[10:11], v[70:71] op_sel_hi:[1,0]
	v_pk_mul_f32 v[8:9], v[8:9], v[70:71] op_sel_hi:[1,0]
	v_pk_mul_f32 v[20:21], v[20:21], v[70:71] op_sel_hi:[1,0]
	v_pk_mul_f32 v[18:19], v[18:19], v[70:71] op_sel_hi:[1,0]
	s_waitcnt lgkmcnt(6)
	v_mfma_f32_16x16x32_f16 v[8:11], v[174:177], v[246:249], v[8:11]
	v_pk_mul_f32 v[6:7], v[6:7], v[70:71] op_sel_hi:[1,0]
	v_pk_mul_f32 v[4:5], v[4:5], v[70:71] op_sel_hi:[1,0]
	s_waitcnt lgkmcnt(5)
	v_mfma_f32_16x16x32_f16 v[18:21], v[150:153], v[246:249], v[18:21]
	v_pk_mul_f32 v[2:3], v[2:3], v[70:71] op_sel_hi:[1,0]
	v_pk_mul_f32 v[0:1], v[0:1], v[70:71] op_sel_hi:[1,0]
	s_waitcnt lgkmcnt(4)
	v_mfma_f32_16x16x32_f16 v[4:7], v[194:197], v[246:249], v[4:7]
	s_waitcnt lgkmcnt(3)
	v_mfma_f32_16x16x32_f16 v[0:3], v[198:201], v[246:249], v[0:3]
	s_waitcnt lgkmcnt(0)
	s_branch .LBB0_259
